# v81 with cold-path padding so hot loops keep v79's code placement (placement experiment)
# speedup vs baseline: 1.0098x; 1.0063x over previous
; #define LAS __attribute__((address_space(3)))
; DI float silu_f(float x) { return x / (1.0f + __expf(-x)); }
; DI void tok0_mix_dil(ldsp lds, const Params& p, const float* P, float* BRo, int task, int tid, int wid, int lane) {
;     const int b = task >> 2, hm = task & 3;
;     const float* pr = P + (size_t)b * 8192;
;     LAS float* OUT = (LAS float*)(lds + 65536); LAS float* S18 = OUT + 64;
;     tok0_mem(lds, pr + DB_QM + hm * 64, p.mem + (size_t)b * 256 * 1024, p.mem_norm_w, p.w_memkv + (size_t)1024 * 512, hm, OUT, tid, wid, lane);
;     if (tid < 64) BRo[(size_t)b * 1024 + 768 + hm * 64 + tid] = OUT[tid] * silu_f(pr[DB_GATE + 768 + hm * 64 + tid]);
;     if (hm == 0) {
;         for (int pi = wid; pi < 18; pi += 8) {
;             const int g = pi / 6, head = pi - g * 6;
;             const float* qp = pr + g * 2304 + head * 128; const float* kp = qp + 768;
;             const float t = wave_sum(qp[lane] * kp[lane] + qp[64 + lane] * kp[64 + lane]) * 0.08838834764831845f;
;             if (lane == 0) S18[pi] = t;
;         }
;         __syncthreads();
;         for (int c = tid; c < 768; c += 512) {
; __global__ void __launch_bounds__(NTHREADS, 2) megak(Params p) {
;     ...
;                 for (int t = blockIdx.x; t < BATCH * 4; t += gridDim.x) tok0_mix_dil(lds, p, T0P, T0BR, t, tid, wid, lane);
.LBB0_91:
	s_andn2_b64 vcc, exec, s[40:41]
	s_cbranch_vccnz .LBB0_126
	v_readlane_b32 s14, v251, 45
	v_readlane_b32 s15, v251, 46
	s_andn2_b64 vcc, exec, s[14:15]
	s_waitcnt vmcnt(0) lgkmcnt(0)
	s_barrier
	s_cbranch_vccnz .LBB0_126
	v_mov_b32_e32 v33, v12
	v_mov_b64_e32 v[30:31], v[32:33]
	v_ashrrev_i32_e32 v33, 31, v32
	v_lshlrev_b64 v[0:1], 11, v[32:33]
	s_mov_b64 s[14:15], 0x100000
	v_lshl_add_u64 v[78:79], v[0:1], 0, s[14:15]
	v_and_b32_e32 v0, 64, v233
	v_add_u32_e32 v0, 64, v0
	v_xor_b32_e32 v1, 32, v233
	v_cmp_lt_i32_e32 vcc, v1, v0
	s_lshl_b32 s22, s16, 5
	v_readlane_b32 s0, v255, 14
	v_cndmask_b32_e32 v1, v233, v1, vcc
	v_lshlrev_b32_e32 v95, 2, v1
	v_xor_b32_e32 v1, 16, v233
	v_cmp_lt_i32_e32 vcc, v1, v0
	s_cmp_lt_u32 s0, 64
	v_lshlrev_b32_e32 v3, 2, v32
	v_cndmask_b32_e32 v1, v233, v1, vcc
	v_lshlrev_b32_e32 v96, 2, v1
	v_xor_b32_e32 v1, 8, v233
	v_cmp_lt_i32_e32 vcc, v1, v0
	v_readlane_b32 s48, v254, 15
	s_cselect_b64 s[46:47], -1, 0
	v_cndmask_b32_e32 v1, v233, v1, vcc
	v_lshlrev_b32_e32 v97, 2, v1
	v_xor_b32_e32 v1, 4, v233
	v_cmp_lt_i32_e32 vcc, v1, v0
	s_add_i32 s0, 0, 0x10000
	v_readlane_b32 s49, v254, 16
	v_cndmask_b32_e32 v1, v233, v1, vcc
	v_lshlrev_b32_e32 v98, 2, v1
	v_xor_b32_e32 v1, 2, v233
	v_cmp_lt_i32_e32 vcc, v1, v0
	v_add_u32_e32 v102, s0, v3
	s_cmp_lt_i32 s16, 18
	v_cndmask_b32_e32 v1, v233, v1, vcc
	v_lshlrev_b32_e32 v99, 2, v1
	v_xor_b32_e32 v1, 1, v233
	v_cmp_lt_i32_e32 vcc, v1, v0
	s_movk_i32 s0, 0x300
	v_lshlrev_b32_e32 v4, 4, v32
	v_cndmask_b32_e32 v0, v233, v1, vcc
	v_ashrrev_i32_e32 v1, 8, v32
	v_lshlrev_b32_e32 v100, 2, v0
	v_lshlrev_b32_e32 v0, 7, v1
	s_cselect_b64 s[48:49], -1, 0
	v_cmp_gt_i32_e64 s[42:43], s0, v32
	s_add_i32 s0, 0, 0x1000
	v_lshlrev_b32_e32 v2, 12, v1
	v_and_b32_e32 v4, 0xff0, v4
	v_ashrrev_i32_e32 v7, 4, v32
	s_lshl_b32 s14, s16, 7
	s_ashr_i32 s23, s22, 31
	v_lshl_add_u32 v104, v1, 9, s0
	v_ashrrev_i32_e32 v1, 31, v0
	v_add_u32_e32 v13, 0, v3
	v_add3_u32 v101, 0, v2, v4
	v_lshlrev_b32_e32 v2, 5, v7
	s_add_i32 s15, s0, s14
	s_lshl_b64 s[22:23], s[22:23], 12
	v_readlane_b32 s17, v254, 14
	v_lshlrev_b64 v[0:1], 12, v[0:1]
	v_and_b32_e32 v3, 0xff, v32
	v_readlane_b32 s50, v254, 17
	v_readlane_b32 s51, v254, 18
	s_add_u32 s22, s17, s22
	v_readlane_b32 s17, v254, 31
	v_lshl_or_b32 v0, v3, 4, v0
	v_ashrrev_i32_e32 v3, 31, v2
	s_addc_u32 s23, s17, s23
	v_lshl_add_u64 v[86:87], s[50:51], 0, v[0:1]
	v_lshlrev_b64 v[0:1], 11, v[2:3]
	s_lshl_b32 s0, s16, 2
	v_lshlrev_b64 v[80:81], 2, v[32:33]
	v_readlane_b32 s52, v254, 19
	v_readlane_b32 s53, v254, 20
	v_readlane_b32 s56, v254, 23
	v_readlane_b32 s57, v254, 24
	v_lshl_add_u32 v94, v238, 4, 0
	v_mul_i32_i24_e32 v6, -12, v238
	v_lshl_add_u32 v8, v7, 8, 0
	v_lshlrev_b32_e32 v9, 4, v155
	v_lshlrev_b32_e32 v4, 4, v238
	v_mov_b32_e32 v5, v12
	v_lshl_or_b32 v0, v155, 4, v0
	s_add_i32 s17, s0, 0
	v_cmp_gt_i32_e64 s[38:39], 64, v32
	v_lshl_add_u64 v[82:83], s[52:53], 0, v[80:81]
	v_cmp_eq_u32_e64 s[40:41], 0, v238
	v_add_u32_e32 v103, 0x1f00, v32
	v_lshl_add_u64 v[84:85], s[22:23], 0, v[4:5]
	v_lshl_add_u64 v[88:89], s[56:57], 0, v[0:1]
	v_lshl_add_u32 v105, v7, 7, 0
	s_add_i32 s17, s17, 0x10100
	v_add_u32_e32 v106, v94, v6
	v_add_u32_e32 v107, v8, v9
	v_lshlrev_b32_e32 v108, 2, v238
	s_and_b32 s34, s78, 7
	s_lshl_b32 s34, s34, 4
	s_lshr_b32 s19, s78, 3
	s_or_b32 s34, s34, s19
	s_cmpk_lt_u32 s78, 0x80
	s_cselect_b32 s34, s34, s78
	s_cmpk_eq_u32 s10, 0x100
	s_cselect_b32 s34, s34, s78
	s_nop 0
	s_nop 0
	s_nop 0
	s_nop 0
	s_nop 0
	s_nop 0
	s_nop 0
	s_nop 0
	s_nop 0
	s_nop 0
	s_nop 0
	s_nop 0
	s_nop 0
	s_nop 0
	s_mov_b32 s19, s34
	v_readlane_b32 s54, v254, 21
	v_readlane_b32 s55, v254, 22
	v_readlane_b32 s58, v254, 25
	v_readlane_b32 s59, v254, 26
	v_readlane_b32 s60, v254, 27
	v_readlane_b32 s61, v254, 28
	v_readlane_b32 s62, v254, 29
	v_readlane_b32 s63, v254, 30
	s_branch .LBB0_96

; #define LAS __attribute__((address_space(3)))
; DI bf16_t f2bf(float f) { return (bf16_t)(cvt_pk_bf16(f, 0.f) & 0xffffu); }
; DI void gla_item(ldsp lds, const Params& p, const bf16_t* proj, bf16_t* obuf, const float* q0k0, int jl, int item, int tid, int wid, int lane) {
;     const int half = item & 1, h = (item >> 1) & 3, b = item >> 3;
;     constexpr int O_GL = 0, O_WG = 5120, O_BG = 12800, O_LA = 13312, O_QI = 38912, O_KI = 52224, O_KO = 65536, O_V = 78848, O_AM = 92160, O_ST = 101376;
;     constexpr int S96 = 208, SGL = 80, SAM = 144, SLA = 100;
;     const ldsp GL = lds + O_GL, WG = lds + O_WG, QI = lds + O_QI, KI = lds + O_KI, KO = lds + O_KO, Vl = lds + O_V, AM = lds + O_AM, ST = lds + O_ST;
;     LAS float* BG = (LAS float*)(lds + O_BG);
;     LAS float* LA = (LAS float*)(lds + O_LA);
;     const int li = lane & 15, quad = lane >> 4;
;     {
;         float wv6[6];
; #pragma unroll
;         for (int i = 0; i < 6; ++i) { const int e = tid + i * 512, d = e >> 5, kk = e & 31;
;             wv6[i] = kk < 16 ? p.w_gate_up[(size_t)(jl * 16 + kk) * 384 + h * 96 + d] : 0.f; }
; #pragma unroll
;         for (int i = 0; i < 6; ++i) { const int e = tid + i * 512, d = e >> 5, kk = e & 31; *(LAS bf16_t*)(WG + d * SGL + kk * 2) = f2bf(wv6[i]); }
;     }
;     for (int e = tid; e < 64 * 40; e += 512) *(LAS bf16_t*)(GL + e * 2) = 0;
;     if (tid < 96) BG[tid] = p.b_gate[jl * 384 + h * 96 + tid];
;     float a00;
;     {
;         const float* qp = q0k0 + b * 768 + h * 96; const float* kp = qp + 384;
;         float t = qp[lane] * kp[lane] + (lane < 32 ? qp[64 + lane] * kp[64 + lane] : 0.f);
;         a00 = wave_sum(t) * 0.10206207261596575f;
;     }
;     f32x4 S[6];
; #pragma unroll
;     for (int i = 0; i < 6; ++i) S[i] = (f32x4){0.f, 0.f, 0.f, 0.f};
;     __syncthreads();
;     const int c0 = tid, c1 = tid + 512;
;     const int row0 = c0 / 12, ch0 = c0 - row0 * 12, row1 = c1 / 12, ch1 = c1 - row1 * 12;
;     const bool has1 = tid < 256;
;     u32x4 qreg0, kreg0, vreg0, qreg1 = (u32x4){0u, 0u, 0u, 0u}, kreg1 = qreg1, vreg1 = qreg1, greg = qreg1;
.LBB0_448:
	s_and_b64 vcc, exec, s[22:23]
	s_cbranch_vccz .LBB0_652
	v_readlane_b32 s14, v251, 52
	v_readlane_b32 s15, v251, 53
	v_lshrrev_b32_e32 v145, 4, v238
	v_and_b32_e32 v69, 48, v32
	s_waitcnt vmcnt(0)
	v_or_b32_e32 v1, 48, v238
	s_mov_b32 s70, s93
	s_andn2_b64 vcc, exec, s[14:15]
	v_bfe_u32 v144, v32, 2, 2
	v_lshlrev_b32_e32 v68, 3, v145
	v_add_u32_e32 v89, 0, v69
	v_mul_u32_u24_e32 v93, 0x90, v1
	v_readlane_b32 s76, v255, 15
	s_cbranch_vccnz .LBB0_504
	v_readlane_b32 s40, v254, 15
	v_readlane_b32 s14, v254, 63
	v_and_b32_e32 v0, 31, v32
	v_readlane_b32 s54, v254, 29
	v_readlane_b32 s55, v254, 30
	v_readlane_b32 s15, v255, 0
	v_cmp_gt_u32_e64 s[38:39], 16, v0
	v_lshl_add_u32 v0, s14, 4, v0
	v_mov_b64_e32 v[2:3], s[54:55]
	s_movk_i32 s22, 0x600
	s_mul_i32 s0, s14, 0x180
	v_mad_u64_u32 v[70:71], s[14:15], v0, s22, v[2:3]
	v_add_u32_e32 v2, 0x800, v32
	v_ashrrev_i32_e32 v80, 5, v2
	v_add_u32_e32 v2, 0xa00, v32
	v_lshlrev_b32_e32 v147, 1, v32
	v_ashrrev_i32_e32 v82, 5, v2
	v_and_b32_e32 v2, 62, v147
	v_and_b32_e32 v11, 64, v233
	v_add_u32_e32 v13, 0, v2
	v_add_u32_e32 v2, 64, v11
	v_xor_b32_e32 v3, 32, v233
	v_cmp_lt_i32_e32 vcc, v3, v2
	v_add_u32_e32 v0, 0x200, v32
	v_add_u32_e32 v34, 0x400, v32
	v_cndmask_b32_e32 v3, v233, v3, vcc
	v_lshlrev_b32_e32 v150, 2, v3
	v_xor_b32_e32 v3, 16, v233
	v_cmp_lt_i32_e32 vcc, v3, v2
	v_add_u32_e32 v35, 0x600, v32
	v_add_u32_e32 v148, s0, v32
	v_cndmask_b32_e32 v3, v233, v3, vcc
	v_lshlrev_b32_e32 v151, 2, v3
	v_xor_b32_e32 v3, 8, v233
	v_cmp_lt_i32_e32 vcc, v3, v2
	s_mov_b32 s0, 0x2aaaaaab
	v_ashrrev_i32_e32 v72, 5, v32
	v_cndmask_b32_e32 v3, v233, v3, vcc
	v_lshlrev_b32_e32 v152, 2, v3
	v_xor_b32_e32 v3, 4, v233
	v_cmp_lt_i32_e32 vcc, v3, v2
	v_ashrrev_i32_e32 v74, 5, v0
	v_ashrrev_i32_e32 v76, 5, v34
	v_cndmask_b32_e32 v3, v233, v3, vcc
	v_lshlrev_b32_e32 v153, 2, v3
	v_xor_b32_e32 v3, 2, v233
	v_cmp_lt_i32_e32 vcc, v3, v2
	v_ashrrev_i32_e32 v78, 5, v35
	s_movk_i32 s14, 0x50
	v_cndmask_b32_e32 v3, v233, v3, vcc
	v_lshlrev_b32_e32 v155, 2, v3
	v_xor_b32_e32 v3, 1, v233
	v_cmp_lt_i32_e32 vcc, v3, v2
	v_readlane_b32 s41, v254, 16
	v_mul_lo_u32 v18, v72, s14
	v_cndmask_b32_e32 v2, v233, v3, vcc
	v_lshlrev_b32_e32 v156, 2, v2
	v_mul_hi_i32 v2, v32, s0
	v_mul_lo_u32 v19, v74, s14
	v_mul_lo_u32 v20, v76, s14
	v_mul_lo_u32 v21, v78, s14
	v_mul_lo_u32 v22, v80, s14
	v_mul_lo_u32 v23, v82, s14
	s_movk_i32 s14, 0xa00
	v_lshrrev_b32_e32 v3, 31, v2
	v_ashrrev_i32_e32 v2, 1, v2
	v_readlane_b32 s42, v254, 17
	v_readlane_b32 s43, v254, 18
	v_cmp_gt_i32_e64 s[40:41], s14, v32
	s_movk_i32 s14, 0x60
	v_add_u32_e32 v84, v2, v3
	v_cmp_gt_i32_e64 s[42:43], s14, v32
	v_mad_u64_u32 v[2:3], s[14:15], v84, -12, v[32:33]
	v_mul_hi_i32 v3, v0, s0
	v_readlane_b32 s46, v254, 21
	v_readlane_b32 s47, v254, 22
	v_lshrrev_b32_e32 v4, 31, v3
	v_ashrrev_i32_e32 v3, 1, v3
	s_movk_i32 s0, 0x100
	v_readlane_b32 s48, v254, 23
	v_readlane_b32 s49, v254, 24
	v_add_u32_e32 v86, v3, v4
	v_cmp_gt_i32_e64 s[46:47], s0, v32
	s_movk_i32 s0, 0x80
	s_cmp_lt_i32 s16, 6
	v_readlane_b32 s31, v255, 14
	v_mad_u64_u32 v[4:5], s[14:15], v86, -12, v[0:1]
	v_cmp_gt_i32_e64 s[48:49], s0, v32
	s_cselect_b64 s[36:37], -1, 0
	s_bfe_u32 s0, s31, 0x20006
	s_lshl_b32 s14, s0, 5
	v_readlane_b32 s19, v254, 48
	s_add_i32 s14, s19, s14
	v_and_b32_e32 v146, 15, v32
	v_add_u32_e32 v26, s14, v68
	s_lshl_b32 s14, s0, 4
	s_movk_i32 s23, 0xd0
	v_or_b32_e32 v3, s14, v146
	v_mad_u32_u24 v27, v3, s23, 0
	v_lshlrev_b32_e32 v3, 4, v32
	s_lshl_b32 s26, s16, 4
	v_and_b32_e32 v10, 16, v3
	v_or_b32_e32 v3, s26, v146
	v_add_u32_e32 v14, -16, v233
	v_lshl_or_b32 v17, v145, 2, s14
	v_lshl_add_u32 v92, v3, 2, 0
	s_movk_i32 s14, 0x4c
	v_cmp_lt_i32_e32 vcc, v14, v11
	v_mad_u64_u32 v[94:95], s[14:15], v3, s14, v[92:93]
	s_nop 0
	v_cndmask_b32_e32 v14, v14, v233, vcc
	v_lshlrev_b32_e32 v95, 2, v14
	v_subrev_u32_e32 v14, 32, v233
	v_cmp_lt_i32_e32 vcc, v14, v11
	s_movk_i32 s14, 0xffb4
	v_mul_lo_u32 v5, v84, s23
	v_cndmask_b32_e32 v14, v14, v233, vcc
	v_lshlrev_b32_e32 v163, 2, v14
	v_mad_u64_u32 v[14:15], s[14:15], v3, s14, v[94:95]
	v_mul_lo_u32 v3, v3, s23
	v_readlane_b32 s14, v254, 49
	v_readlane_b32 s17, v254, 47
	v_mul_lo_u32 v30, v86, s23
	v_add_u32_e32 v165, s14, v3
	v_lshlrev_b32_e32 v3, 2, v238
	v_and_b32_e32 v15, 12, v3
	v_or_b32_e32 v3, s26, v15
	v_add_u32_e32 v24, s17, v5
	v_add_u32_e32 v31, s17, v30
	v_lshl_add_u32 v37, v3, 1, s17
	s_movk_i32 s17, 0x190
	v_mul_lo_u32 v3, v84, s17
	v_lshlrev_b32_e32 v6, 3, v2
	v_lshlrev_b32_e32 v25, 4, v2
	v_add_u32_e32 v16, 0, v3
	v_lshlrev_b32_e32 v2, 5, v2
	s_movk_i32 s30, 0xff40
	v_add_u32_e32 v38, s19, v69
	v_add_u32_e32 v166, v16, v2
	v_add_u32_e32 v167, 0, v2
	v_mad_u64_u32 v[2:3], s[14:15], v84, s30, v[16:17]
	s_add_i32 s19, 0, 0x10000
	v_add_u32_e32 v3, s19, v5
	v_mul_lo_u32 v5, v86, s17
	v_lshlrev_b32_e32 v8, 3, v4
	v_lshlrev_b32_e32 v36, 4, v4
	v_add_u32_e32 v16, 0, v5
	v_lshlrev_b32_e32 v4, 5, v4
	v_add_u32_e32 v168, v16, v4
	v_add_u32_e32 v169, 0, v4
	v_mad_u64_u32 v[4:5], s[14:15], v86, s30, v[16:17]
	s_ashr_i32 s27, s26, 31
	s_ashr_i32 s14, s31, 8
	s_cmp_le_i32 s0, s14
	s_cselect_b64 s[30:31], -1, 0
	s_add_i32 s17, s16, 8
	v_or_b32_e32 v11, v11, v1
	v_mul_u32_u24_e32 v41, 0x50, v1
	v_add_u32_e32 v5, s19, v30
	v_lshl_or_b32 v30, s14, 4, v146
	s_ashr_i32 s14, s17, 2
	s_waitcnt lgkmcnt(0)
; DI void gla_item(ldsp lds, const Params& p, const bf16_t* proj, bf16_t* obuf, const float* q0k0, int jl, int item, int tid, int wid, int lane) {
;     ...
;     const int c0 = tid, c1 = tid + 512;
;     const int row0 = c0 / 12, ch0 = c0 - row0 * 12, row1 = c1 / 12, ch1 = c1 - row1 * 12;
;     const bool has1 = tid < 256;
;     u32x4 qreg0, kreg0, vreg0, qreg1 = (u32x4){0u, 0u, 0u, 0u}, kreg1 = qreg1, vreg1 = qreg1, greg = qreg1;
;     ...
;     GLA_LOAD_CHUNK(0);
;     for (int n = 0; n < 32; ++n) {
; __global__ void __launch_bounds__(NTHREADS, 2) megak(Params p) {
;     ...
;                 for (int it = blockIdx.x; it < BATCH * 8; it += gridDim.x) gla_item(lds, p, PROJ, OBUF, Q0K0, jl, it, tid, wid, lane);
	v_mul_u32_u24_e32 v45, 0xd0, v1
	v_max_i32_e32 v1, 0x800, v32
	v_mul_lo_u32 v16, v30, s23
	s_cmp_le_i32 s0, s14
	v_lshl_or_b32 v33, s14, 4, v146
	v_sub_u32_e32 v1, v1, v32
	v_add_u32_e32 v42, 0, v16
	s_cselect_b64 s[72:73], -1, 0
	v_mul_lo_u32 v16, v33, s23
	s_lshl_b64 s[14:15], s[26:27], 1
	v_add_u32_e32 v47, 0x1ff, v1
	v_ashrrev_i32_e32 v9, 31, v8
	v_or_b32_e32 v28, 2, v17
	v_or_b32_e32 v29, 3, v17
	v_lshlrev_b32_e32 v164, 2, v11
	v_or_b32_e32 v11, v68, v144
	v_cmp_gt_i32_e64 s[54:55], v17, v30
	v_cmp_lt_i32_e64 s[56:57], v17, v30
	v_add_u32_e32 v43, 0, v16
	v_cmp_gt_i32_e64 s[62:63], v17, v33
	v_cmp_lt_i32_e64 s[64:65], v17, v33
	v_mov_b64_e32 v[16:17], s[14:15]
	s_movk_i32 s0, 0x90
	v_lshrrev_b32_e32 v1, 9, v47
	v_readlane_b32 s14, v251, 15
	v_cmp_gt_i32_e64 s[58:59], v28, v30
	v_cmp_gt_i32_e64 s[66:67], v28, v33
	v_cmp_gt_i32_e64 s[68:69], v29, v33
	v_mul_u32_u24_e32 v28, 0xd0, v11
	v_mul_lo_u32 v46, v33, s0
	v_add_u32_e32 v48, 1, v1
	v_mov_b32_e32 v33, v0
	v_mov_b32_e32 v11, v12
	v_readlane_b32 s15, v251, 16
	v_lshlrev_b64 v[98:99], 1, v[8:9]
	v_mov_b64_e32 v[0:1], 0x68a0600
	s_waitcnt lgkmcnt(0)
	v_ashrrev_i32_e32 v7, 31, v6
	v_lshl_add_u64 v[96:97], s[14:15], 0, v[10:11]
	v_mad_i64_i32 v[100:101], s[14:15], v86, s94, v[0:1]
	v_mad_i64_i32 v[104:105], s[14:15], v86, s94, v[98:99]
	v_and_b32_e32 v0, 1, v32
	v_mov_b32_e32 v1, 0x68a0c00
	v_lshl_or_b32 v106, v0, 4, v1
	v_lshlrev_b64 v[108:109], 1, v[6:7]
	s_mov_b64 s[14:15], 0x68a0600
	v_mov_b64_e32 v[0:1], s[6:7]
	v_lshl_add_u64 v[110:111], v[108:109], 0, s[14:15]
	v_mad_i64_i32 v[112:113], s[14:15], v84, s94, v[0:1]
	v_mul_u32_u24_e32 v6, 0x600, v146
	v_lshrrev_b32_e32 v0, 1, v69
	v_mad_i64_i32 v[114:115], s[14:15], v84, s94, v[108:109]
	v_or_b32_e32 v116, v6, v0
	v_mad_u64_u32 v[6:7], s[14:15], v146, s22, v[16:17]
	v_cmp_gt_i32_e64 s[60:61], v29, v30
	v_mul_lo_u32 v30, v30, s0
	s_mov_b64 s[14:15], 0x26840000
	s_movk_i32 s0, 0x5ff
	v_lshl_add_u64 v[118:119], v[6:7], 0, s[14:15]
	v_cmp_lt_u32_e64 s[14:15], s0, v47
	v_and_b32_e32 v170, 0xfffffc, v48
	v_readlane_b32 s44, v254, 19
	v_writelane_b32 v255, s14, 17
	v_readlane_b32 s45, v254, 20
	v_readlane_b32 s50, v254, 25
	v_writelane_b32 v255, s15, 18
	v_cmp_ne_u32_e64 s[14:15], v48, v170
	v_readlane_b32 s51, v254, 26
	v_readlane_b32 s52, v254, 27
	v_readlane_b32 s53, v254, 28
	v_ashrrev_i32_e32 v90, 1, v32
	v_mul_u32_u24_e32 v39, 0x50, v146
	v_mul_u32_u24_e32 v40, 0x640, v145
	v_lshl_add_u32 v15, v15, 1, s19
	v_mul_u32_u24_e32 v29, 0x90, v146
	v_mul_u32_u24_e32 v44, 0xd0, v146
	v_mov_b32_e32 v1, v12
	v_writelane_b32 v255, s14, 19
	v_ashrrev_i32_e32 v73, 31, v72
	v_ashrrev_i32_e32 v75, 31, v74
	v_ashrrev_i32_e32 v77, 31, v76
	v_ashrrev_i32_e32 v79, 31, v78
	v_ashrrev_i32_e32 v81, 31, v80
	v_ashrrev_i32_e32 v83, 31, v82
	s_movk_i32 s71, 0x50
	v_lshl_add_u32 v149, v32, 2, 0
	v_cmp_gt_u32_e64 s[44:45], 32, v238
	v_ashrrev_i32_e32 v85, 31, v84
	v_ashrrev_i32_e32 v87, 31, v86
	v_lshrrev_b32_e32 v88, 1, v32
	v_ashrrev_i32_e32 v91, 31, v90
	v_cmp_gt_u32_e64 s[50:51], 16, v238
	v_add_u32_e32 v162, 0, v10
	v_cmp_lt_u32_e64 s[52:53], 31, v238
	v_lshl_add_u32 v171, v170, 9, v32
	v_lshl_add_u64 v[102:103], s[6:7], 0, v[98:99]
	v_mov_b32_e32 v107, v12
	v_mul_hi_u32_u24_e32 v117, 0x600, v146
	v_lshl_add_u64 v[120:121], s[6:7], 0, v[0:1]
	v_add_u32_e32 v172, v13, v18
	v_add_u32_e32 v173, v13, v19
	v_add_u32_e32 v174, v13, v20
	v_add_u32_e32 v175, v13, v21
	v_add_u32_e32 v176, v13, v22
	v_add_u32_e32 v177, v13, v23
	v_lshlrev_b32_e32 v122, 2, v238
	v_add_u32_e32 v178, v24, v25
	v_add_u32_e32 v179, v31, v36
	v_add_u32_e32 v180, v89, v39
	v_add_u32_e32 v181, v14, v40
	v_add_u32_e32 v182, v89, v41
	v_add_u32_e32 v183, v2, v25
	v_add_u32_e32 v184, v3, v25
	v_add_u32_e32 v185, v4, v36
	v_add_u32_e32 v186, v5, v36
	v_add_u32_e32 v187, v42, v69
	v_add_u32_e32 v188, v26, v30
	v_add_u32_e32 v189, v43, v69
	v_add_u32_e32 v190, v26, v46
	v_add_u32_e32 v191, v37, v28
	v_add_u32_e32 v192, v38, v29
	v_add_u32_e32 v193, v38, v93
	v_add_u32_e32 v194, v89, v44
	v_add_u32_e32 v195, v89, v45
	v_add_u32_e32 v196, v15, v28
	v_add_u32_e32 v197, v27, v69
	v_readlane_b32 s19, v254, 54
	v_writelane_b32 v255, s15, 20
	s_and_b32 s98, s19, 7
	s_lshl_b32 s98, s98, 5
	s_lshr_b32 s99, s19, 3
	s_or_b32 s98, s98, s99
	s_cmpk_eq_u32 s10, 0x100
	s_cselect_b32 s19, s98, s19
	s_nop 0
	s_nop 0
	s_nop 0
	s_nop 0
	s_nop 0
	s_nop 0
	s_nop 0
	s_nop 0
	s_nop 0
	s_nop 0
	s_nop 0
	s_nop 0
	s_nop 0
	s_nop 0
	s_branch .LBB0_452

; #define LAS __attribute__((address_space(3)))
; DI float silu_f(float x) { return x / (1.0f + __expf(-x)); }
; DI void tok0_mix_gla(ldsp lds, const Params& p, const float* P, float* BRo, int task, int tid, int wid, int lane) {
;     const int b = task >> 2, hm = task & 3;
;     const float* pr = P + (size_t)b * 8192;
;     LAS float* OUT = (LAS float*)(lds + 65536); LAS float* R3 = OUT + 64;
;     tok0_mem(lds, pr + GA_QM + hm * 64, p.mem + (size_t)b * 256 * 1024, p.mem_norm_w, p.w_memkv, hm, OUT, tid, wid, lane);
;     if (tid < 64) BRo[(size_t)b * 1024 + 768 + hm * 64 + tid] = OUT[tid] * silu_f(pr[GA_GATE + 768 + hm * 64 + tid]);
;     const float* qp = pr + hm * 96; const float* kp = pr + GA_K + hm * 96;
;     const float a = wave_sum(qp[lane] * kp[lane] + (lane < 32 ? qp[64 + lane] * kp[64 + lane] : 0.f)) * 0.10206207261596575f;
;     float ve = 0.f;
;     if (tid < 192) ve = pr[GA_V + hm * 192 + tid];
;     const float sq = wave_sum(ve * ve);
;     if (lane == 0 && wid < 3) R3[wid] = sq;
;     __syncthreads();
;     const float msv = (R3[0] + R3[1] + R3[2]) * (1.0f / 192.0f);
;     const float rs = rsqrtf(a * a * msv + 1e-6f);
;     if (tid < 192) BRo[(size_t)b * 1024 + hm * 192 + tid] = a * ve * rs * p.gla_norm_w[tid] * silu_f(pr[GA_GATE + hm * 192 + tid]);
; __global__ void __launch_bounds__(NTHREADS, 2) megak(Params p) {
;     ...
;                 if (L == 0) for (int t = blockIdx.x; t < BATCH * 4; t += gridDim.x) tok0_mix_gla(lds, p, T0P, T0BR, t, tid, wid, lane);
.LBB0_827:
	v_readlane_b32 s14, v251, 43
	v_readlane_b32 s18, v255, 7
	v_readlane_b32 s15, v251, 44
	v_readlane_b32 s19, v255, 8
	s_or_b64 s[14:15], s[18:19], s[14:15]
	s_and_b64 vcc, exec, s[14:15]
	s_cbranch_vccnz .LBB0_860
	v_and_b32_e32 v2, 64, v233
	v_add_u32_e32 v2, 64, v2
	v_xor_b32_e32 v4, 32, v233
	v_cmp_lt_i32_e32 vcc, v4, v2
	s_lshl_b32 s22, s16, 5
	v_readlane_b32 s0, v255, 14
	v_cndmask_b32_e32 v4, v233, v4, vcc
	v_lshlrev_b32_e32 v97, 2, v4
	v_xor_b32_e32 v4, 16, v233
	v_cmp_lt_i32_e32 vcc, v4, v2
	v_lshlrev_b64 v[0:1], 11, v[32:33]
	s_mov_b64 s[14:15], 0x100000
	v_cndmask_b32_e32 v4, v233, v4, vcc
	v_lshlrev_b32_e32 v98, 2, v4
	v_xor_b32_e32 v4, 8, v233
	v_cmp_lt_i32_e32 vcc, v4, v2
	s_cmp_lt_u32 s0, 64
	v_lshlrev_b32_e32 v3, 2, v32
	v_cndmask_b32_e32 v4, v233, v4, vcc
	v_lshlrev_b32_e32 v99, 2, v4
	v_xor_b32_e32 v4, 4, v233
	v_cmp_lt_i32_e32 vcc, v4, v2
	v_lshl_add_u64 v[78:79], v[0:1], 0, s[14:15]
	v_readlane_b32 s44, v254, 15
	v_cndmask_b32_e32 v4, v233, v4, vcc
	v_lshlrev_b32_e32 v100, 2, v4
	v_xor_b32_e32 v4, 2, v233
	v_cmp_lt_i32_e32 vcc, v4, v2
	s_cselect_b64 s[14:15], -1, 0
	s_add_i32 s0, 0, 0x10000
	v_readlane_b32 s45, v254, 16
	v_cndmask_b32_e32 v4, v233, v4, vcc
	v_add_u32_e32 v104, s0, v3
	s_movk_i32 s0, 0xc0
	s_cmp_lt_i32 s16, 3
	v_lshlrev_b32_e32 v101, 2, v4
	v_xor_b32_e32 v4, 1, v233
	v_cmp_gt_i32_e64 s[44:45], s0, v32
	s_cselect_b64 s[18:19], -1, 0
	s_lshl_b32 s0, s16, 2
	v_readlane_b32 s56, v254, 27
	v_readlane_b32 s57, v254, 28
	v_readlane_b32 s58, v254, 29
	v_readlane_b32 s59, v254, 30
	v_cmp_lt_i32_e32 vcc, v4, v2
	v_cmp_eq_u32_e64 s[40:41], 0, v238
	s_add_i32 s17, s0, 0
	s_lshl_b32 s0, s16, 7
	s_add_i32 s26, 0, 0x1000
	s_ashr_i32 s23, s22, 31
	v_cndmask_b32_e32 v2, v233, v4, vcc
	v_ashrrev_i32_e32 v5, 8, v32
	v_lshlrev_b32_e32 v7, 4, v32
	s_and_b64 s[18:19], s[40:41], s[18:19]
	s_add_i32 s17, s17, 0x10100
	v_readlane_b32 s56, v251, 0
	s_add_i32 s34, s26, s0
	s_lshl_b64 s[22:23], s[22:23], 12
	v_readlane_b32 s0, v254, 14
	v_lshlrev_b64 v[0:1], 2, v[32:33]
	v_readlane_b32 s48, v254, 19
	v_readlane_b32 s49, v254, 20
	v_lshlrev_b32_e32 v102, 2, v2
	v_lshlrev_b32_e32 v2, 7, v5
	v_lshlrev_b32_e32 v4, 12, v5
	v_and_b32_e32 v7, 0xff0, v7
	v_readlane_b32 s58, v251, 2
	v_readlane_b32 s59, v251, 3
	s_add_u32 s22, s0, s22
	v_readlane_b32 s0, v254, 31
	v_add_u32_e32 v13, 0, v3
	v_lshl_add_u64 v[80:81], s[48:49], 0, v[0:1]
	v_add3_u32 v103, 0, v4, v7
	v_ashrrev_i32_e32 v7, 4, v32
	v_lshl_add_u64 v[82:83], s[58:59], 0, v[0:1]
	v_lshlrev_b32_e32 v0, 4, v238
	v_mov_b32_e32 v1, v12
	s_addc_u32 s23, s0, s23
	v_ashrrev_i32_e32 v3, 31, v2
	v_lshlrev_b32_e32 v4, 5, v7
	v_lshl_add_u64 v[84:85], s[22:23], 0, v[0:1]
	v_lshlrev_b64 v[0:1], 12, v[2:3]
	v_and_b32_e32 v2, 0xff, v32
	v_readlane_b32 s46, v254, 17
	v_readlane_b32 s47, v254, 18
	v_lshl_add_u32 v107, v5, 9, s26
	v_lshl_or_b32 v0, v2, 4, v0
	v_ashrrev_i32_e32 v5, 31, v4
	v_lshl_add_u64 v[86:87], s[46:47], 0, v[0:1]
	v_lshlrev_b64 v[0:1], 11, v[4:5]
	v_readlane_b32 s52, v254, 23
	v_readlane_b32 s53, v254, 24
	v_lshl_add_u32 v96, v238, 4, 0
	v_mul_i32_i24_e32 v6, -12, v238
	v_lshl_add_u32 v8, v7, 8, 0
	v_lshlrev_b32_e32 v9, 4, v155
	v_lshl_or_b32 v0, v155, 4, v0
	v_cmp_gt_i32_e64 s[38:39], 64, v32
	v_mov_b32_e32 v30, v32
	v_mov_b32_e32 v31, v12
	v_add_u32_e32 v105, 0xa10, v32
	v_cmp_gt_u32_e64 s[42:43], 32, v238
	v_add_u32_e32 v106, 0x710, v32
	v_lshl_add_u64 v[88:89], s[52:53], 0, v[0:1]
	v_lshl_add_u32 v108, v7, 7, 0
	v_add_u32_e32 v109, v96, v6
	v_add_u32_e32 v110, v8, v9
	v_lshlrev_b32_e32 v90, 2, v238
	s_and_b32 s36, s78, 7
	s_lshl_b32 s36, s36, 4
	s_lshr_b32 s35, s78, 3
	s_or_b32 s36, s36, s35
	s_cmpk_lt_u32 s78, 0x80
	s_cselect_b32 s36, s36, s78
	s_cmpk_eq_u32 s10, 0x100
	s_cselect_b32 s36, s36, s78
	s_nop 0
	s_nop 0
	s_nop 0
	s_nop 0
	s_nop 0
	s_nop 0
	s_nop 0
	s_nop 0
	s_nop 0
	s_nop 0
	s_nop 0
	s_nop 0
	s_nop 0
	s_nop 0
	s_mov_b32 s35, s36
	v_readlane_b32 s50, v254, 21
	v_readlane_b32 s51, v254, 22
	v_readlane_b32 s54, v254, 25
	v_readlane_b32 s55, v254, 26
	v_readlane_b32 s57, v251, 1
	v_readlane_b32 s60, v251, 4
	v_readlane_b32 s61, v251, 5
	v_readlane_b32 s62, v251, 6
	v_readlane_b32 s63, v251, 7
	s_branch .LBB0_830
